# stagger (odd XCDs later) in all five GEMM phases: P2/P4/P9 +3.5 us, P7/P10 +7 us
# speedup vs baseline: 1.0054x; 1.0054x over previous
.LBB0_306:
	v_readlane_b32 s16, v252, 0
	v_bfe_u32 v18, v0, 4, 2
	v_readlane_b32 s31, v252, 15
	v_and_b32_e32 v17, 15, v0
	v_lshlrev_b32_e32 v19, 4, v18
	v_lshlrev_b32_e32 v20, 2, v0
	s_and_b32 s31, s0, 3
	v_lshl_or_b32 v19, v17, 6, v19
	s_lshl_b32 s0, s7, 13
	v_and_b32_e32 v20, 32, v20
	v_readlane_b32 s26, v252, 10
	v_readlane_b32 s30, v252, 14
	v_readlane_b32 s4, v255, 10
	v_bitop3_b32 v21, v19, s0, v20 bitop3:0xde
	s_lshl_b32 s0, s31, 12
	s_add_i32 m0, s65, 0x18000
	v_lshl_add_u64 v[8:9], v[8:9], 0, s[56:57]
	s_lshl_b32 s16, s4, 6
	s_lshl_b32 s6, s7, 6
	s_lshl_b32 s26, s31, 5
	v_bitop3_b32 v188, v19, s0, v20 bitop3:0xde
	s_waitcnt vmcnt(4)
	s_barrier
	global_load_lds_dwordx4 v[8:9], off
	v_lshl_add_u64 v[6:7], v[6:7], 0, s[56:57]
	s_add_i32 m0, s65, 0x1a000
	s_add_i32 s30, s65, 0x8000
	s_add_i32 s0, s65, 0xa000
	v_readlane_b32 s5, v255, 11
	global_load_lds_dwordx4 v[6:7], off
	v_lshl_add_u64 v[4:5], v[4:5], 0, s[56:57]
	s_mov_b32 m0, s30
	s_add_u32 s4, s14, 0x40080
	global_load_lds_dwordx4 v[4:5], off
	v_lshl_add_u64 v[2:3], v[2:3], 0, s[56:57]
	s_mov_b32 m0, s0
	s_addc_u32 s5, s15, 0
	global_load_lds_dwordx4 v[2:3], off
	s_add_i32 m0, s65, 0x1c000
	v_lshl_add_u64 v[2:3], s[4:5], 0, v[164:165]
	global_load_lds_dwordx4 v[2:3], off
	s_add_i32 m0, s65, 0x1e000
	v_lshl_add_u64 v[2:3], s[4:5], 0, v[168:169]
	s_cmp_lt_u32 s31, 2
	global_load_lds_dwordx4 v[2:3], off
	s_cselect_b64 s[4:5], -1, 0
	v_and_b32_e32 v2, 16, v0
	v_writelane_b32 v255, s4, 19
	s_cmp_eq_u32 s31, 0
	v_cmp_eq_u32_e64 s[44:45], 0, v2
	v_or_b32_e32 v2, 16, v17
	v_writelane_b32 v255, s5, 20
	s_cselect_b64 s[4:5], -1, 0
	v_cvt_f32_ubyte0_e32 v190, v2
	v_or_b32_e32 v2, 32, v17
	v_lshlrev_b32_e32 v170, 3, v18
	v_writelane_b32 v255, s4, 21
	v_cvt_f32_ubyte0_e32 v191, v2
	v_or_b32_e32 v2, 48, v17
	v_writelane_b32 v255, s5, 22
	s_lshl_b32 s8, s31, 6
	s_or_b32 s9, s26, 0x80
	v_cvt_f32_ubyte0_e32 v192, v2
	v_and_b32_e32 v2, 8, v170
	v_writelane_b32 v255, s9, 23
	s_mov_b32 s39, s8
	s_or_b32 s8, s8, 32
	v_cvt_f32_ubyte0_e32 v3, v2
	v_writelane_b32 v255, s8, 24
	v_mul_f32_e32 v4, 0xbf549a78, v3
	s_mov_b32 s8, 0xc2fc0000
	v_cmp_gt_f32_e32 vcc, s8, v4
	v_mov_b32_e32 v6, 0x42800000
	v_not_b32_e32 v7, 63
	v_cndmask_b32_e32 v4, 0, v6, vcc
	v_fmac_f32_e32 v4, 0xbf549a78, v3
	v_exp_f32_e32 v3, v4
	v_or_b32_e32 v4, 1, v2
	v_cvt_f32_ubyte0_e32 v4, v4
	v_mul_f32_e32 v5, 0xbf549a78, v4
	v_cmp_gt_f32_e64 s[10:11], s8, v5
	v_readlane_b32 s27, v252, 11
	s_add_i32 s27, s7, -4
	v_cndmask_b32_e64 v5, 0, v6, s[10:11]
	v_fmac_f32_e32 v5, 0xbf549a78, v4
	v_exp_f32_e32 v4, v5
	v_cndmask_b32_e32 v5, 0, v7, vcc
	v_ldexp_f32 v193, v3, v5
	v_cndmask_b32_e64 v3, 0, v7, s[10:11]
	v_ldexp_f32 v194, v4, v3
	v_or_b32_e32 v3, 2, v2
	v_cvt_f32_ubyte0_e32 v3, v3
	v_mul_f32_e32 v4, 0xbf549a78, v3
	v_cmp_gt_f32_e32 vcc, s8, v4
	s_lshl_b32 s7, s7, 2
	s_or_b32 s7, s7, s31
	v_cndmask_b32_e32 v4, 0, v6, vcc
	v_fmac_f32_e32 v4, 0xbf549a78, v3
	v_exp_f32_e32 v3, v4
	v_or_b32_e32 v4, 3, v2
	v_cvt_f32_ubyte0_e32 v4, v4
	v_mul_f32_e32 v5, 0xbf549a78, v4
	v_cmp_gt_f32_e64 s[10:11], s8, v5
	v_readlane_b32 s17, v252, 1
	v_readlane_b32 s18, v252, 2
	v_cndmask_b32_e64 v5, 0, v6, s[10:11]
	v_fmac_f32_e32 v5, 0xbf549a78, v4
	v_exp_f32_e32 v4, v5
	v_cndmask_b32_e32 v5, 0, v7, vcc
	v_ldexp_f32 v195, v3, v5
	v_cndmask_b32_e64 v3, 0, v7, s[10:11]
	v_ldexp_f32 v196, v4, v3
	v_or_b32_e32 v3, 4, v2
	v_cvt_f32_ubyte0_e32 v3, v3
	v_mul_f32_e32 v4, 0xbf549a78, v3
	v_cmp_gt_f32_e32 vcc, s8, v4
	v_readlane_b32 s19, v252, 3
	v_readlane_b32 s20, v252, 4
	v_cndmask_b32_e32 v4, 0, v6, vcc
	v_fmac_f32_e32 v4, 0xbf549a78, v3
	v_exp_f32_e32 v3, v4
	v_or_b32_e32 v4, 5, v2
	v_cvt_f32_ubyte0_e32 v4, v4
	v_mul_f32_e32 v5, 0xbf549a78, v4
	v_cmp_gt_f32_e64 s[10:11], s8, v5
	v_readlane_b32 s21, v252, 5
	v_readlane_b32 s22, v252, 6
	v_cndmask_b32_e64 v5, 0, v6, s[10:11]
	v_fmac_f32_e32 v5, 0xbf549a78, v4
	v_exp_f32_e32 v4, v5
	v_cndmask_b32_e32 v5, 0, v7, vcc
	v_ldexp_f32 v197, v3, v5
	v_cndmask_b32_e64 v3, 0, v7, s[10:11]
	v_ldexp_f32 v198, v4, v3
	v_or_b32_e32 v3, 6, v2
	v_cvt_f32_ubyte0_e32 v3, v3
	v_mul_f32_e32 v4, 0xbf549a78, v3
	v_cmp_gt_f32_e32 vcc, s8, v4
	v_or_b32_e32 v2, 7, v2
	v_cvt_f32_ubyte0_e32 v2, v2
	v_cndmask_b32_e32 v4, 0, v6, vcc
	v_fmac_f32_e32 v4, 0xbf549a78, v3
	v_exp_f32_e32 v3, v4
	v_mul_f32_e32 v4, 0xbf549a78, v2
	v_cmp_gt_f32_e64 s[10:11], s8, v4
	s_mov_b32 s8, 0x12000
	v_mul_u32_u24_e32 v5, 0x140, v18
	v_cndmask_b32_e64 v4, 0, v6, s[10:11]
	v_fmac_f32_e32 v4, 0xbf549a78, v2
	v_exp_f32_e32 v2, v4
	v_cndmask_b32_e32 v4, 0, v7, vcc
	v_ldexp_f32 v199, v3, v4
	v_cndmask_b32_e64 v3, 0, v7, s[10:11]
	v_ldexp_f32 v200, v2, v3
	s_mul_i32 s10, s7, 0xa00
	v_bfe_u32 v3, v0, 1, 5
	v_and_b32_e32 v0, 16, v13
	v_or_b32_e32 v4, s26, v3
	v_mov_b32_e32 v6, 0x900000
	s_add_i32 s10, s10, 0
	v_mul_u32_u24_e32 v2, 0x12000, v4
	v_mad_u32_u24 v4, v4, s8, v6
	s_add_i32 s10, s10, 0x20040
	v_mul_u32_u24_e32 v3, 0x50, v3
	v_lshlrev_b32_e32 v6, 1, v0
	v_readlane_b32 s23, v252, 7
	v_readlane_b32 s25, v252, 9
	s_lshr_b32 s8, s34, 3
	v_add3_u32 v201, s10, v3, v6
	v_lshlrev_b32_e32 v3, 1, v5
	v_lshlrev_b32_e32 v5, 1, v17
	s_mov_b32 s9, s17
	v_readlane_b32 s24, v252, 8
	v_readlane_b32 s28, v252, 12
	v_readlane_b32 s29, v252, 13
	s_mov_b32 s67, s17
	s_mov_b32 s25, s17
	v_writelane_b32 v255, s8, 25
	v_add3_u32 v202, s10, v3, v5
	v_writelane_b32 v252, s8, 0
	v_lshlrev_b32_e32 v3, 14, v10
	v_and_b32_e32 v3, 0xffff8000, v3
	v_writelane_b32 v252, s9, 1
	v_writelane_b32 v252, s10, 2
	v_writelane_b32 v252, s11, 3
	v_writelane_b32 v252, s12, 4
	v_writelane_b32 v252, s13, 5
	v_writelane_b32 v252, s14, 6
	v_writelane_b32 v252, s15, 7
	v_writelane_b32 v252, s16, 8
	v_writelane_b32 v252, s17, 9
	v_writelane_b32 v252, s18, 10
	v_writelane_b32 v252, s19, 11
	v_writelane_b32 v252, s20, 12
	v_writelane_b32 v252, s21, 13
	v_writelane_b32 v252, s22, 14
	v_lshl_add_u32 v3, v11, 11, v3
	v_and_b32_e32 v5, 1, v10
	v_writelane_b32 v252, s23, 15
	s_lshl_b64 s[8:9], s[16:17], 2
	v_lshl_or_b32 v3, v5, 6, v3
	v_writelane_b32 v255, s8, 26
	v_lshl_add_u32 v172, v12, 1, v3
	v_lshlrev_b32_e32 v3, 14, v14
	v_writelane_b32 v255, s9, 27
	v_and_b32_e32 v3, 0xffff8000, v3
	v_writelane_b32 v255, s44, 28
	s_waitcnt vmcnt(6)
	v_cmp_eq_u32_e64 s[46:47], 0, v18
	v_lshl_add_u32 v3, v15, 11, v3
	v_and_b32_e32 v5, 1, v14
	v_writelane_b32 v255, s45, 29
	s_ashr_i32 s7, s6, 31
	v_lshl_or_b32 v3, v5, 6, v3
	v_writelane_b32 v255, s46, 30
	v_or_b32_e32 v171, s6, v17
	s_mov_b32 s1, 0
	v_cmp_gt_u32_e64 s[4:5], 2, v18
	v_cvt_f32_ubyte0_e32 v189, v17
	s_mov_b32 s24, s34
	v_mov_b32_e32 v173, v1
	v_lshl_add_u32 v174, v16, 1, v3
	v_mov_b32_e32 v175, v1
	v_add_u32_e32 v203, 0, v21
	v_lshlrev_b32_e32 v176, 2, v170
	s_lshl_b64 s[84:85], s[6:7], 1
	v_lshlrev_b32_e32 v178, 1, v0
	v_lshlrev_b32_e32 v180, 1, v2
	v_lshlrev_b32_e32 v182, 1, v4
	v_writelane_b32 v255, s47, 31
	s_barrier
	s_bitcmp1_b32 s54, 0
	s_cbranch_scc0 .Lstg_p2_0
	s_sleep 127
.Lstg_p2_0:
	s_branch .LBB0_308
.LBB0_307:
	s_and_b64 vcc, exec, s[10:11]
	s_mov_b32 s88, s90
	s_mov_b32 s86, s8
	s_mov_b64 s[14:15], s[6:7]
	s_mov_b64 s[12:13], s[36:37]
	s_cbranch_vccnz .LBB0_456

.LBB0_514:
	v_lshl_add_u64 v[12:13], s[12:13], 0, v[0:1]
	v_mov_b32_e32 v179, v1
	v_readlane_b32 s10, v254, 29
	s_lshl_b32 s1, s1, 5
	v_lshl_add_u64 v[14:15], s[12:13], 0, v[178:179]
	v_mov_b32_e32 v183, v1
	v_readlane_b32 s11, v254, 30
	s_and_b32 s1, s1, 0x60
	s_add_i32 m0, s24, 0x18000
	v_lshl_add_u64 v[12:13], v[12:13], 0, s[56:57]
	v_lshl_add_u64 v[16:17], s[10:11], 0, v[182:183]
	v_mov_b32_e32 v181, v1
	s_lshl_b32 s8, s0, 13
	s_lshl_b32 s9, s1, 7
	s_waitcnt vmcnt(4)
	s_barrier
	global_load_lds_dwordx4 v[12:13], off
	v_lshl_add_u64 v[12:13], v[14:15], 0, s[56:57]
	s_add_i32 m0, s24, 0x1a000
	s_add_i32 s34, s24, 0x8000
	s_add_i32 s35, s24, 0xa000
	v_lshl_add_u64 v[18:19], s[10:11], 0, v[180:181]
	global_load_lds_dwordx4 v[12:13], off
	v_lshl_add_u64 v[12:13], v[16:17], 0, s[56:57]
	s_mov_b32 m0, s34
	s_add_u32 s6, s12, 0x20080
	global_load_lds_dwordx4 v[12:13], off
	v_lshl_add_u64 v[12:13], v[18:19], 0, s[56:57]
	s_mov_b32 m0, s35
	s_addc_u32 s7, s13, 0
	global_load_lds_dwordx4 v[12:13], off
	s_add_i32 m0, s24, 0x1c000
	v_lshl_add_u64 v[12:13], s[6:7], 0, v[0:1]
	global_load_lds_dwordx4 v[12:13], off
	v_lshl_add_u64 v[12:13], s[6:7], 0, v[178:179]
	s_add_i32 m0, s24, 0x1e000
	v_and_b32_e32 v11, 15, v2
	global_load_lds_dwordx4 v[12:13], off
	v_lshrrev_b32_e32 v12, 1, v2
	v_and_b32_e32 v12, 24, v12
	v_lshlrev_b32_e32 v13, 1, v12
	v_lshlrev_b32_e32 v2, 2, v2
	v_lshl_or_b32 v235, s0, 6, v11
	v_lshl_or_b32 v11, v11, 6, v13
	v_and_b32_e32 v2, 32, v2
	v_bitop3_b32 v13, v11, s8, v2 bitop3:0xde
	v_bitop3_b32 v236, v11, s9, v2 bitop3:0xde
	v_or_b32_e32 v237, s1, v12
	v_lshrrev_b32_e32 v2, 1, v8
	s_movk_i32 s1, 0x7a00
	s_movk_i32 s0, 0x7a0
	v_mul_lo_u32 v2, v2, s1
	v_mul_lo_u32 v7, v7, s0
	v_add3_u32 v2, v2, v7, v9
	v_add_lshl_u32 v8, v2, v10, 1
	v_lshrrev_b32_e32 v2, 1, v3
	v_mul_lo_u32 v2, v2, s1
	v_mul_lo_u32 v3, v4, s0
	s_waitcnt vmcnt(6)
	v_add3_u32 v2, v2, v3, v5
	v_mov_b32_e32 v9, v1
	s_mov_b64 s[6:7], 0x7a080
	v_add_lshl_u32 v2, v2, v6, 1
	v_mov_b32_e32 v3, v1
	v_lshl_add_u64 v[184:185], v[8:9], 0, s[6:7]
	v_lshl_add_u64 v[186:187], v[2:3], 0, s[6:7]
	s_mov_b32 s61, 0
	v_add_u32_e32 v238, 0, v13
	v_readlane_b32 s21, v254, 23
	v_readlane_b32 s20, v254, 28
	s_barrier
	s_bitcmp1_b32 s54, 0
	s_cbranch_scc0 .Lstg_p4_0
	s_sleep 127
.Lstg_p4_0:
	s_branch .LBB0_517
.LBB0_515:
	s_or_b64 exec, exec, s[10:11]
